# G1 second-round tiles go to the first workgroup of each CU (run-time HW_ID census, unique dense indices, dynamic-queue fallback) instead of the dynamic dequeue
# speedup vs baseline: 1.1231x; 1.0092x over previous
.Llayout_posted:
	s_or_b64 exec, exec, s[100:101]
	s_and_saveexec_b64 s[100:101], s[14:15]
	s_cbranch_execz .Lcu_census_done
	s_getreg_b32 s98, hwreg(HW_REG_HW_ID)
	s_bfe_u32 s98, s98, 0x80008
	s_and_b32 s99, s2, 7
	s_lshl_b32 s99, s99, 8
	s_or_b32 s98, s98, s99
	s_lshl_b32 s98, s98, 2
	v_mov_b32_e32 v2, s98
	v_mov_b32_e32 v3, 1
	s_add_u32 s98, s10, 0xc200
	s_addc_u32 s99, s11, 0
	global_atomic_add v2, v2, v3, s[98:99] sc0
	s_waitcnt vmcnt(0)
	v_readfirstlane_b32 s98, v2
	v_mov_b32_e32 v2, 0x7fff
	s_cmp_lg_u32 s98, 0
	s_cbranch_scc1 .Lcu_census_store
	s_and_b32 s99, s2, 7
	s_lshl_b32 s99, s99, 2
	v_mov_b32_e32 v2, s99
	s_add_u32 s98, s10, 0xc180
	s_addc_u32 s99, s11, 0
	global_atomic_add v2, v2, v3, s[98:99] sc0
	s_waitcnt vmcnt(0)
.Lcu_census_store:
	s_lshl_b32 s98, s2, 2
	v_mov_b32_e32 v3, s98
	s_add_u32 s98, s10, 0xe400
	s_addc_u32 s99, s11, 0
	global_store_dword v3, v2, s[98:99] sc1

.LBB0_291:
	s_add_u32 s98, s74, 0x18934600
	s_addc_u32 s99, s75, 0
	v_and_b32_e32 v0, 7, v160
	v_lshlrev_b32_e32 v0, 2, v0
	global_load_dword v0, v0, s[98:99] sc1
	s_waitcnt vmcnt(0)
	v_bcnt_u32_b32 v0, v0, 0
	v_cmp_ne_u32_e32 vcc, 1, v0
	s_cmp_lg_u64 vcc, 0
	s_cselect_b32 s98, 1, 0
	v_writelane_b32 v255, s98, 63
	s_add_u32 s98, s74, 0x18936900
	s_addc_u32 s99, s75, 0
	s_lshl_b32 s100, s2, 2
	v_mov_b32_e32 v0, s100
	global_load_dword v0, v0, s[98:99] sc1
	s_waitcnt vmcnt(0)
	v_readfirstlane_b32 s100, v0
	s_add_u32 s98, s74, 0x18934680
	s_addc_u32 s99, s75, 0
	s_and_b32 s101, s2, 7
	s_lshl_b32 s101, s101, 2
	v_mov_b32_e32 v0, s101
	global_load_dword v0, v0, s[98:99] sc1
	s_waitcnt vmcnt(0)
	v_readfirstlane_b32 s98, v0
	s_lshr_b32 s99, s33, 3
	s_sub_u32 s99, 96, s99
	s_cmp_lt_i32 s98, s99
	s_cselect_b32 s100, -1, s100
	v_writelane_b32 v255, s100, 62
	s_and_b32 s48, s27, 3
	s_ashr_i32 s5, s2, 3
	s_ashr_i32 s33, s33, 3
	s_lshl_b32 s0, s76, 2
	s_add_u32 s0, s74, s0
	s_addc_u32 s1, s75, 0
	v_writelane_b32 v253, s27, 39
	s_add_u32 s0, s0, 0x1ad38500
	v_writelane_b32 v253, s0, 40
	s_addc_u32 s0, s1, 0
	v_writelane_b32 v253, s0, 41
	s_add_u32 s0, s74, 0x13800000
	s_addc_u32 s1, s75, 0
	v_writelane_b32 v253, s0, 42
	s_mul_i32 s94, s48, 6
	v_mov_b32_e32 v1, 0
	v_writelane_b32 v253, s1, 43
	s_lshl_b32 s0, s48, 6
	v_readlane_b32 s4, v253, 0
	s_lshl_b32 s1, s4, 3
	s_or_b32 s95, s1, 16
	s_lshl_b32 s96, s4, 4
	s_add_u32 s36, s74, 0x14400000
	s_addc_u32 s37, s75, 0
	s_add_u32 s66, s3, 0x4200
	s_addc_u32 s67, s86, 0
	s_add_u32 s80, s3, 0x4400
	s_addc_u32 s81, s86, 0
	s_add_u32 s82, s3, 0x4500
	s_addc_u32 s83, s86, 0
	s_add_u32 s6, s3, 0x4600
	v_writelane_b32 v253, s1, 44
	s_addc_u32 s7, s86, 0
	v_writelane_b32 v253, s6, 45
	s_mulk_i32 s48, 0x300
	v_mov_b32_e32 v161, 0x130b0
	v_writelane_b32 v253, s7, 46
	s_add_u32 s6, s3, 0x4700
	s_addc_u32 s7, s86, 0
	v_writelane_b32 v253, s6, 47
	v_mov_b32_e32 v201, 0x3727c5ac
	v_mbcnt_hi_u32_b32 v202, -1, v60
	v_writelane_b32 v253, s7, 48
	s_add_u32 s6, s3, 0x4800
	s_addc_u32 s7, s86, 0
	v_writelane_b32 v253, s6, 49
	v_mov_b32_e32 v205, 0xfffffc00
	v_mov_b32_e32 v206, 0xffffff00
	v_writelane_b32 v253, s7, 50
	s_add_u32 s6, s3, 0x4900
	s_addc_u32 s7, s86, 0
	v_writelane_b32 v253, s6, 51
	v_mov_b32_e32 v207, 0xe00
	v_mov_b32_e32 v208, 0xe40
	v_writelane_b32 v253, s7, 52
	s_add_u32 s6, s3, 0x4a00
	s_addc_u32 s7, s86, 0
	v_writelane_b32 v253, s6, 53
	v_mov_b32_e32 v209, 0xe60
	v_mov_b32_e32 v210, 0x200
	v_writelane_b32 v253, s7, 54
	s_add_u32 s6, s3, 0x4b00
	s_addc_u32 s7, s86, 0
	v_writelane_b32 v253, s6, 55
	v_mov_b32_e32 v211, 0xff800000
	v_mov_b32_e32 v212, 0xff61b1e6
	v_writelane_b32 v253, s7, 56
	s_add_u32 s6, s3, 0x4c00
	s_addc_u32 s7, s86, 0
	v_writelane_b32 v253, s6, 57
	s_movk_i32 s51, 0x300
	s_movk_i32 s52, 0x800
	v_writelane_b32 v253, s7, 58
	s_add_u32 s6, s3, 0x4d00
	s_addc_u32 s7, s86, 0
	v_writelane_b32 v253, s6, 59
	s_movk_i32 s53, 0x90
	s_mov_b32 s54, 0x10000
	v_writelane_b32 v253, s7, 60
	s_add_u32 s6, s3, 0x4e00
	s_addc_u32 s7, s86, 0
	v_writelane_b32 v253, s6, 61
	s_mov_b32 s55, 0x20000
	s_mov_b32 s56, 0x30000
	v_writelane_b32 v253, s7, 62
	s_add_u32 s6, s3, 0x4f00
	s_addc_u32 s7, s86, 0
	v_writelane_b32 v253, s6, 63
	s_movk_i32 s57, 0xfff
	s_movk_i32 s58, 0x1000
	v_writelane_b32 v254, s7, 0
	s_add_u32 s6, s3, 0x5000
	s_addc_u32 s7, s86, 0
	v_writelane_b32 v254, s6, 1
	s_movk_i32 s59, 0x110
	s_movk_i32 s60, 0x81
	v_writelane_b32 v254, s7, 2
	s_add_u32 s6, s3, 0x5100
	s_addc_u32 s7, s86, 0
	v_writelane_b32 v254, s6, 3
	s_mov_b32 s61, 0xff800000
	s_mov_b32 s62, 0x800000
	v_writelane_b32 v254, s7, 4
	s_add_u32 s6, s3, 0x5200
	s_addc_u32 s7, s86, 0
	s_add_u32 s84, s3, 0x5300
	v_writelane_b32 v254, s6, 5
	s_addc_u32 s85, s86, 0
	s_movk_i32 s63, 0x6000
	v_writelane_b32 v254, s7, 6
	s_add_u32 s6, s3, 0x7400
	s_addc_u32 s7, s86, 0
	v_writelane_b32 v254, s6, 7
	s_movk_i32 s64, 0x2ff
	s_movk_i32 s65, 0xff80
	v_writelane_b32 v254, s7, 8
	s_add_u32 s6, s3, 0x7500
	s_addc_u32 s7, s86, 0
	s_bfe_u32 s1, s2, 0x30001
	v_writelane_b32 v254, s6, 9
	s_lshl_b32 s2, s1, 6
	s_add_i32 s1, s87, s1
	v_writelane_b32 v254, s7, 10
	s_add_u32 s6, s74, 0x15c00000
	v_writelane_b32 v254, s1, 11
	s_addc_u32 s7, s75, 0
	v_writelane_b32 v254, s6, 12
	s_add_u32 s1, s74, 0x18688500
	s_mov_b64 s[88:89], 0x100
	v_writelane_b32 v254, s7, 13
	v_writelane_b32 v254, s1, 14
	s_addc_u32 s1, s75, 0
	v_writelane_b32 v254, s1, 15
	s_add_u32 s1, s74, 0x18788500
	v_writelane_b32 v254, s1, 16
	s_addc_u32 s1, s75, 0
	v_writelane_b32 v254, s1, 17
	s_add_u32 s1, s74, 0x18588500
	v_writelane_b32 v254, s1, 18
	s_addc_u32 s1, s75, 0
	v_writelane_b32 v254, s1, 19
	s_add_u32 s1, s74, 0x18608500
	v_writelane_b32 v254, s1, 20
	s_addc_u32 s1, s75, 0
	v_writelane_b32 v254, s1, 21
	s_add_u32 s1, s74, 0x18588000
	v_writelane_b32 v254, s1, 22
	s_addc_u32 s1, s75, 0
	v_writelane_b32 v254, s1, 23
	s_add_u32 s1, s74, 0x1000000
	v_writelane_b32 v254, s1, 24
	s_addc_u32 s1, s75, 0
	s_add_u32 s92, s74, 0x12000000
	s_addc_u32 s93, s75, 0
	s_add_u32 s6, s74, 0x18002000
	v_writelane_b32 v254, s1, 25
	s_addc_u32 s7, s75, 0
	v_writelane_b32 v254, s6, 26
	s_lshl_b32 s49, s4, 10
	s_lshl_b32 s1, s5, 2
	v_writelane_b32 v254, s7, 27
	v_writelane_b32 v254, s5, 28
	s_lshl_b32 s97, s33, 2
	s_bitset1_b32 s49, 11
	s_lshl_b32 s50, s4, 11
	v_writelane_b32 v254, s1, 29
	s_add_u32 s1, s74, 0x1800000
	v_writelane_b32 v254, s1, 30
	s_addc_u32 s1, s75, 0
	s_add_u32 s34, s74, 0x16800000
	s_addc_u32 s35, s75, 0
	s_add_u32 s4, s74, 0x18928700
	v_writelane_b32 v254, s1, 31
	s_addc_u32 s5, s75, 0
	v_writelane_b32 v254, s4, 32
	s_add_u32 s1, s74, 0x18908500
	s_mov_b64 s[22:23], 0
	v_writelane_b32 v254, s5, 33
	v_writelane_b32 v254, s1, 34
	s_addc_u32 s1, s75, 0
	v_writelane_b32 v254, s1, 35
	s_add_u32 s1, s74, 0x2000000
	v_writelane_b32 v254, s1, 36
	s_addc_u32 s1, s75, 0
	v_writelane_b32 v254, s1, 37
	s_add_u32 s1, s74, 0x18888500
	v_writelane_b32 v254, s1, 38
	s_addc_u32 s1, s75, 0
	v_writelane_b32 v254, s1, 39
	s_add_u32 s1, s74, 0x188c8500
	v_writelane_b32 v254, s1, 40
	s_addc_u32 s1, s75, 0
	s_add_u32 s8, s74, 0x30180
	s_addc_u32 s9, s75, 0
	s_add_u32 s10, s74, 0x10180
	s_addc_u32 s11, s75, 0
	s_add_u32 s12, s74, 0x180
	s_addc_u32 s13, s75, 0
	s_add_u32 s26, s74, 0x100
	s_addc_u32 s27, s75, 0
	s_add_u32 s28, s74, 0x10100
	s_addc_u32 s29, s75, 0
	s_add_u32 s30, s74, 0x20100
	v_writelane_b32 v254, s1, 41
	s_addc_u32 s31, s75, 0
	s_lshl_b32 s0, s0, 2
	v_writelane_b32 v254, s0, 42
	s_lshl_b32 s0, s2, 2
	s_mov_b64 s[4:5], s[72:73]
	v_writelane_b32 v254, s0, 43
	s_mov_b64 s[6:7], s[74:75]
	v_writelane_b32 v254, s0, 44
	s_mov_b32 s86, 0x3fd744fd
	s_mov_b32 s18, s21
	v_writelane_b32 v254, s1, 45
	v_writelane_b32 v254, s2, 46
	v_writelane_b32 v254, s3, 47
	v_writelane_b32 v254, s4, 48
	v_writelane_b32 v254, s5, 49
	v_writelane_b32 v254, s6, 50
	v_writelane_b32 v254, s7, 51
	v_writelane_b32 v254, s66, 52
	s_nop 1
	v_writelane_b32 v254, s67, 53
	v_writelane_b32 v254, s80, 54
	s_nop 1
	v_writelane_b32 v254, s81, 55
	v_writelane_b32 v254, s82, 56
	s_nop 1
	v_writelane_b32 v254, s83, 57
	v_writelane_b32 v254, s34, 58
	s_nop 1
	v_writelane_b32 v254, s35, 59
	s_branch .LBB0_295

.LBB0_410:
	s_or_b64 exec, exec, s[0:1]
	s_lshl_b32 s101, s33, 1
	s_cmp_lt_u32 s101, 96
	s_cbranch_scc1 .Lg1_fetch
	s_cmp_ge_u32 s100, s33
	s_cbranch_scc1 .LBB0_415
	v_readlane_b32 s101, v255, 62
	s_nop 0
	s_cmp_eq_u32 s101, -1
	s_cbranch_scc1 .Lg1_fetch
	s_add_i32 s101, s101, s33
	s_cmp_gt_u32 s101, 95
	s_cbranch_scc1 .LBB0_415
	s_waitcnt vmcnt(63) expcnt(7) lgkmcnt(15)
	s_barrier
	v_mov_b32_e32 v0, s101
	s_branch .LBB0_297
